# attention: the 16 p0 exp2 after barrier 1 deferred into the next QK region (fill the LDS-read bubble before the first MFMA)
# baseline (speedup 1.0000x reference)
; #define SBAR() __builtin_amdgcn_sched_barrier(0)
; __device__ __forceinline__ int v_st(int k, int c) { const int kk = (k & ~0xC) | ((k & 4) << 1) | ((k & 8) >> 1); return ((kk >> 3) * 4 + (c >> 5)) * 512 + ((kk & 7) * 32 + (c & 31)) * 2; }
; __device__ __forceinline__ int v_rd_base(int lane) { return ((lane & 3) << 3) | (((lane >> 2) & 3) << 6) | (((lane >> 4) & 1) << 5) | (((lane >> 5) & 1) << 8); }
; #define VMW() asm volatile("s_waitcnt vmcnt(0)" ::: "memory")
; #define SLOAD_H(Kp, Vp, k0) do { S.st_v0 = load8(ROW(Vp, k0, sr)); S.st_v1 = load8(ROW(Vp, k0, 32 + sr));              \
;                          S.st_k0 = load8(ROW(Kp, k0, sr)); S.st_k1 = load8(ROW(Kp, k0, 32 + sr)); } while (0)
; #define SWRITE_HV(bf) do { *(bf16x8*)(V_lds + (bf) * SHM_V + vst0) = S.st_v0; *(bf16x8*)(V_lds + (bf) * SHM_V + vst1) = S.st_v1; } while (0)
; #define SWRITE_H(bf) do { SWRITE_HV(bf); SWRITE_HK(bf); } while (0)
; #define MASKT(P0_, P1_) sel_mask_tile(P0_, P1_, mw.x, mw.y, hi)
; __device__ __forceinline__ void attn_block(const BlockRef& cur, const BlockRef& nxt, char* lds, Seam& S) {
;     const int tid = threadIdx.x, wid = __builtin_amdgcn_readfirstlane(tid >> 6), lane = tid & 63, r32 = lane & 31, hi = lane >> 5;
;     const int NT = (cur.P0 + QB - 1) / KVBLK + 1;
;     char* V_lds = lds; char* K_lds = lds + 2 * SHM_V;
;     float* ws = (float*)(lds + 2 * SHM_V + 2 * SHM_K) + wid * 64; float* li_l = ws, * al_l = ws + 32;
;     float m_reg = -1e30f, l_reg = 0; f32x16 o[4] = {};
;     const int sr = tid >> 4, sc = (tid & 15) * 8, vst0 = v_st(sr, sc), vst1 = v_st(32 + sr, sc), kws = KSWZ(sr, sc * 2);
;     const int vb0 = (int)(uintptr_t)V_lds + v_rd_base(lane);
;     const bf16* Kh = cur.K; const bf16* Vh = cur.V;
;     const unsigned mrow_off = (unsigned)(wid * QBLK + r32) * 512u;
;     u32x2 mw;
;     ...
;     constexpr int NQL = 8;
;     ...
;     f32x16 pA0, pA1, pB0, pB1; float mnA, mnB, alA, alB; bf16x8 pa0, pa1, pa2, pa3;
;     SWRITE_HV(0); SBAR();
;     mw = LDMASK(0);
;     if (NT > 1) { SLOAD_H(Kh, Vh, KBASE(1)); }
;     SBAR(); qkt<0>(pA0, pA1, K_lds, r32, hi, S.qr);
;     MASKT(pA0, pA1); partialSM(pA0, pA1, m_reg, mnA, alA);
;     if (NT > 1) { VMW(); SWRITE_H(1); }
;     __syncthreads();
.LBB0_1298:
	v_readfirstlane_b32 s83, v0
	s_lshr_b32 s12, s38, 6
	s_or_b32 s81, s12, 3
	s_and_b32 s12, s83, 0x3fffffc0
	s_lshl_b32 s12, s12, 2
	s_add_i32 s84, s12, 0
	s_lshr_b32 s12, s83, 1
	s_and_b32 s12, s12, 0x7fffffe0
	v_and_b32_e32 v88, 31, v0
	v_or_b32_e32 v186, s12, v88
	s_mov_b32 s82, 1
	v_lshlrev_b32_e32 v165, 9, v186
	s_add_i32 s84, s84, 0x10000
	s_waitcnt vmcnt(1)
	ds_write_b128 v197, v[130:133]
	s_waitcnt vmcnt(0)
	ds_write_b128 v198, v[134:137]
	v_mov_b32_e32 v183, v167
	v_lshl_add_u64 v[2:3], s[70:71], 0, v[182:183]
	v_mov_b32_e32 v177, v167
	v_mov_b32_e32 v185, v167
	v_lshl_add_u64 v[2:3], v[2:3], 0, v[176:177]
	v_lshl_add_u64 v[4:5], s[70:71], 0, v[184:185]
	global_load_dwordx2 v[86:87], v165, s[68:69]
	v_lshl_add_u64 v[4:5], v[4:5], 0, v[176:177]
	global_load_dwordx4 v[50:53], v[2:3], off
	global_load_dwordx4 v[54:57], v[4:5], off
	v_lshl_add_u64 v[2:3], s[6:7], 0, v[182:183]
	v_lshl_add_u64 v[2:3], v[2:3], 0, v[176:177]
	v_lshl_add_u64 v[4:5], s[6:7], 0, v[184:185]
	v_lshl_add_u64 v[4:5], v[4:5], 0, v[176:177]
	global_load_dwordx4 v[58:61], v[2:3], off
	global_load_dwordx4 v[62:65], v[4:5], off
	ds_read_b128 v[2:5], v199 offset:32768
	ds_read_b128 v[6:9], v199 offset:32896
	s_mov_b32 s36, s13
	s_mov_b32 s37, s13
	s_mov_b32 s38, s13
	s_waitcnt lgkmcnt(1)
	v_mfma_f32_32x32x16_bf16 v[34:49], v[2:5], v[126:129], 0
	ds_read_b128 v[2:5], v199 offset:40960
	ds_read_b128 v[10:13], v199 offset:41088
	s_mov_b32 s39, s13
	s_mov_b32 s40, s13
	s_mov_b32 s41, s13
	s_mov_b32 s42, s13
	s_mov_b32 s43, s13
	s_mov_b32 s44, s13
	s_waitcnt lgkmcnt(1)
	v_mfma_f32_32x32x16_bf16 v[18:33], v[2:5], v[126:129], 0
	ds_read_b128 v[2:5], v200 offset:32768
	ds_read_b128 v[14:17], v200 offset:32896
	s_mov_b32 s45, s13
	s_mov_b32 s46, s13
	s_mov_b32 s47, s13
	s_mov_b32 s48, s13
	s_mov_b32 s49, s13
	s_mov_b32 s50, s13
	s_waitcnt lgkmcnt(1)
	v_mfma_f32_32x32x16_bf16 v[34:49], v[2:5], v[122:125], v[34:49]
	ds_read_b128 v[2:5], v200 offset:40960
	ds_read_b128 v[66:69], v200 offset:41088
	s_mov_b32 s51, s13
	v_lshl_add_u32 v185, v88, 2, s84
	v_lshl_add_u32 v183, v163, 2, s84
	v_lshl_add_u64 v[188:189], s[70:71], 0, v[252:253]
	v_lshl_add_u64 v[190:191], s[6:7], 0, v[252:253]
	v_mov_b32_e32 v205, 0
	s_waitcnt lgkmcnt(1)
	v_mfma_f32_32x32x16_bf16 v[18:33], v[2:5], v[122:125], v[18:33]
	ds_read_b128 v[2:5], v201 offset:32768
	ds_read_b128 v[70:73], v201 offset:32896
	s_waitcnt lgkmcnt(1)
	v_mfma_f32_32x32x16_bf16 v[34:49], v[2:5], v[118:121], v[34:49]
	ds_read_b128 v[2:5], v201 offset:40960
	ds_read_b128 v[74:77], v201 offset:41088
	s_waitcnt lgkmcnt(1)
	v_mfma_f32_32x32x16_bf16 v[18:33], v[2:5], v[118:121], v[18:33]
	ds_read_b128 v[2:5], v202 offset:32768
	ds_read_b128 v[78:81], v202 offset:32896
	s_waitcnt lgkmcnt(1)
	v_mfma_f32_32x32x16_bf16 v[34:49], v[2:5], v[114:117], v[34:49]
	ds_read_b128 v[2:5], v202 offset:40960
	ds_read_b128 v[82:85], v202 offset:41088
	s_waitcnt vmcnt(0)
	s_waitcnt vmcnt(3)
	ds_write_b128 v197, v[50:53] offset:16384
	s_waitcnt vmcnt(2)
	ds_write_b128 v198, v[54:57] offset:16384
	s_waitcnt vmcnt(1)
	ds_write_b128 v204, v[58:61] offset:49152
	s_waitcnt vmcnt(0)
	ds_write_b128 v204, v[62:65] offset:57344
	s_waitcnt lgkmcnt(0)
	s_barrier
	v_mfma_f32_32x32x16_bf16 v[34:49], v[6:9], v[110:113], v[34:49]
	v_mfma_f32_32x32x16_bf16 v[18:33], v[2:5], v[114:117], v[18:33]
	v_mfma_f32_32x32x16_bf16 v[34:49], v[14:17], v[106:109], v[34:49]
	v_mfma_f32_32x32x16_bf16 v[18:33], v[10:13], v[110:113], v[18:33]
	v_mov_b64_e32 v[2:3], s[36:37]
	v_mov_b64_e32 v[4:5], s[38:39]
	v_mov_b64_e32 v[6:7], s[40:41]
	v_mov_b64_e32 v[8:9], s[42:43]
	v_mov_b64_e32 v[10:11], s[44:45]
	v_mov_b64_e32 v[12:13], s[46:47]
	v_mov_b64_e32 v[14:15], s[48:49]
	v_mfma_f32_32x32x16_bf16 v[34:49], v[70:73], v[102:105], v[34:49]
	v_mov_b64_e32 v[16:17], s[50:51]
	v_mov_b64_e32 v[64:65], v[16:17]
	v_mov_b64_e32 v[62:63], v[14:15]
	v_mov_b64_e32 v[60:61], v[12:13]
	v_mov_b64_e32 v[58:59], v[10:11]
	v_mov_b64_e32 v[56:57], v[8:9]
	v_mov_b64_e32 v[54:55], v[6:7]
	v_mfma_f32_32x32x16_bf16 v[18:33], v[66:69], v[106:109], v[18:33]
	v_lshrrev_b32_e32 v66, v163, v86
	v_bfe_i32 v68, v66, 0, 1
	v_lshrrev_b32_e32 v67, v163, v87
	v_bfe_i32 v69, v67, 0, 1
	v_bfe_i32 v70, v67, 2, 1
	v_bfe_i32 v71, v67, 3, 1
	v_bfe_i32 v72, v67, 8, 1
	v_mfma_f32_32x32x16_bf16 v[34:49], v[78:81], v[98:101], v[34:49]
	v_bfe_i32 v73, v67, 9, 1
	v_bfe_i32 v78, v67, 18, 1
	v_bfe_i32 v79, v67, 19, 1
	v_bfe_i32 v80, v67, 24, 1
	v_bfe_i32 v81, v67, 25, 1
	v_mov_b64_e32 v[52:53], v[4:5]
	v_mov_b64_e32 v[50:51], v[2:3]
	v_mfma_f32_32x32x16_bf16 v[18:33], v[74:77], v[102:105], v[18:33]
	s_nop 3
	v_bitop3_b32 v68, v34, s74, v68 bitop3:0xe4
	v_bfe_i32 v34, v66, 1, 1
	v_bitop3_b32 v35, v35, s74, v34 bitop3:0xe4
	v_bfe_i32 v34, v66, 2, 1
	v_bitop3_b32 v36, v36, s74, v34 bitop3:0xe4
	v_bfe_i32 v34, v66, 3, 1
	v_bitop3_b32 v37, v37, s74, v34 bitop3:0xe4
	v_bfe_i32 v34, v66, 8, 1
	v_bitop3_b32 v38, v38, s74, v34 bitop3:0xe4
	v_bfe_i32 v34, v66, 9, 1
	v_bitop3_b32 v39, v39, s74, v34 bitop3:0xe4
	v_bfe_i32 v34, v66, 10, 1
	v_bitop3_b32 v40, v40, s74, v34 bitop3:0xe4
	v_bfe_i32 v34, v66, 11, 1
	v_mfma_f32_32x32x16_bf16 v[18:33], v[82:85], v[98:101], v[18:33]
	v_bitop3_b32 v41, v41, s74, v34 bitop3:0xe4
	v_bfe_i32 v34, v66, 16, 1
	v_bitop3_b32 v42, v42, s74, v34 bitop3:0xe4
	v_bfe_i32 v34, v66, 17, 1
	v_bitop3_b32 v43, v43, s74, v34 bitop3:0xe4
	v_bfe_i32 v34, v66, 18, 1
	v_bitop3_b32 v44, v44, s74, v34 bitop3:0xe4
	v_bfe_i32 v34, v66, 19, 1
	v_bitop3_b32 v45, v45, s74, v34 bitop3:0xe4
	v_bfe_i32 v34, v66, 24, 1
	v_bitop3_b32 v46, v46, s74, v34 bitop3:0xe4
	v_bfe_i32 v34, v66, 25, 1
	v_bitop3_b32 v47, v47, s74, v34 bitop3:0xe4
; __device__ __forceinline__ void partialSM(f32x16& p0, f32x16& p1, float& m_reg, float& mn, float& alpha) {
;     float pmax = p0[0];
; #pragma unroll
;     for (int r = 1; r < 16; ++r) pmax = fmaxf(pmax, p0[r]);
; #pragma unroll
;     for (int r = 0; r < 16; ++r) pmax = fmaxf(pmax, p1[r]);
;     { auto rr = __builtin_amdgcn_permlane32_swap(__float_as_uint(pmax), __float_as_uint(pmax), false, false);
;       pmax = fmaxf(__uint_as_float(rr[0]), __uint_as_float(rr[1])); }
;     constexpr float C2 = 1.4426950408889634f * SCALE;
;     if (__builtin_expect(__all((pmax - m_reg) * SCALE <= THR), 1)) { mn = m_reg; alpha = 1.f; }
;     else { mn = fmaxf(m_reg, pmax); alpha = __builtin_amdgcn_exp2f((m_reg - mn) * C2); m_reg = mn; }
;     const float mnL = -mn * C2;
; #pragma unroll
;     for (int r = 0; r < 16; ++r) p0[r] = fmaf(p0[r], C2, mnL);
; #pragma unroll
;     for (int r = 0; r < 16; ++r) p1[r] = fmaf(p1[r], C2, mnL);
; #pragma unroll
;     for (int r = 0; r < 16; ++r) p0[r] = __builtin_amdgcn_exp2f(p0[r]);
; }
	v_bfe_i32 v34, v66, 26, 1
	v_bitop3_b32 v48, v48, s74, v34 bitop3:0xe4
	v_bfe_i32 v34, v66, 27, 1
	v_bitop3_b32 v18, v18, s74, v69 bitop3:0xe4
	v_bfe_i32 v69, v67, 1, 1
	v_bfe_i32 v74, v67, 10, 1
	v_bfe_i32 v75, v67, 11, 1
	v_bfe_i32 v76, v67, 16, 1
	v_bfe_i32 v77, v67, 17, 1
	v_bfe_i32 v82, v67, 26, 1
	v_bfe_i32 v66, v67, 27, 1
	v_bitop3_b32 v49, v49, s74, v34 bitop3:0xe4
	v_max_f32_e32 v34, v35, v35
	v_max_f32_e32 v67, v68, v68
	v_max_f32_e32 v34, v67, v34
	v_max3_f32 v34, v34, v36, v37
	v_max3_f32 v34, v34, v38, v39
	v_max3_f32 v34, v34, v40, v41
	v_max3_f32 v34, v34, v42, v43
	v_max3_f32 v34, v34, v44, v45
	v_max3_f32 v34, v34, v46, v47
	v_max3_f32 v34, v34, v48, v49
	v_bitop3_b32 v19, v19, s74, v69 bitop3:0xe4
	v_bitop3_b32 v20, v20, s74, v70 bitop3:0xe4
	v_max3_f32 v34, v34, v18, v19
	v_bitop3_b32 v21, v21, s74, v71 bitop3:0xe4
	v_bitop3_b32 v22, v22, s74, v72 bitop3:0xe4
	v_max3_f32 v34, v34, v20, v21
	v_bitop3_b32 v23, v23, s74, v73 bitop3:0xe4
	v_bitop3_b32 v24, v24, s74, v74 bitop3:0xe4
	v_max3_f32 v34, v34, v22, v23
	v_bitop3_b32 v25, v25, s74, v75 bitop3:0xe4
	v_bitop3_b32 v26, v26, s74, v76 bitop3:0xe4
	v_max3_f32 v34, v34, v24, v25
	v_bitop3_b32 v27, v27, s74, v77 bitop3:0xe4
	v_bitop3_b32 v28, v28, s74, v78 bitop3:0xe4
	v_max3_f32 v34, v34, v26, v27
	v_bitop3_b32 v29, v29, s74, v79 bitop3:0xe4
	v_bitop3_b32 v30, v30, s74, v80 bitop3:0xe4
	v_max3_f32 v34, v34, v28, v29
	v_bitop3_b32 v31, v31, s74, v81 bitop3:0xe4
	v_bitop3_b32 v32, v32, s74, v82 bitop3:0xe4
	v_max3_f32 v34, v34, v30, v31
	v_bitop3_b32 v33, v33, s74, v66 bitop3:0xe4
	v_max3_f32 v34, v34, v32, v33
	v_mov_b32_e32 v66, v34
	s_nop 1
	v_permlane32_swap_b32_e32 v34, v66
	v_max_f32_e32 v66, v66, v66
	v_max_f32_e32 v34, v34, v34
	v_max_f32_e32 v34, v34, v66
	v_add_f32_e32 v66, 0x7149f2ca, v34
	v_mul_f32_e32 v66, 0x3db504f3, v66
	v_max_f32_e32 v34, 0xf149f2ca, v34
	v_cmp_ge_f32_e32 vcc, s75, v66
	v_sub_f32_e32 v66, 0xf149f2ca, v34
	v_mul_f32_e32 v66, 0x3e0293ee, v66
	s_cmp_eq_u64 vcc, exec
	v_exp_f32_e32 v66, v66
	s_cselect_b64 vcc, -1, 0
	v_cndmask_b32_e32 v206, v34, v203, vcc
	v_mul_f32_e32 v34, 0xbe0293ee, v206
	v_mov_b32_e32 v67, v34
	v_cndmask_b32_e64 v177, v66, 1.0, vcc
	v_fmamk_f32 v66, v68, 0x3e0293ee, v34
	v_fmamk_f32 v35, v35, 0x3e0293ee, v34
	v_fmamk_f32 v36, v36, 0x3e0293ee, v34
	v_fmamk_f32 v37, v37, 0x3e0293ee, v34
	v_fmamk_f32 v38, v38, 0x3e0293ee, v34
	v_fmamk_f32 v39, v39, 0x3e0293ee, v34
	v_fmamk_f32 v40, v40, 0x3e0293ee, v34
	v_fmamk_f32 v41, v41, 0x3e0293ee, v34
	v_fmamk_f32 v42, v42, 0x3e0293ee, v34
	v_fmamk_f32 v43, v43, 0x3e0293ee, v34
	v_fmamk_f32 v44, v44, 0x3e0293ee, v34
	v_fmamk_f32 v45, v45, 0x3e0293ee, v34
	v_fmamk_f32 v46, v46, 0x3e0293ee, v34
	v_fmamk_f32 v47, v47, 0x3e0293ee, v34
	v_fmamk_f32 v48, v48, 0x3e0293ee, v34
	v_fmac_f32_e32 v67, 0x3e0293ee, v49
	v_exp_f32_e32 v219, v66
	v_exp_f32_e32 v220, v35
	v_exp_f32_e32 v221, v36
	v_exp_f32_e32 v222, v37
	v_exp_f32_e32 v223, v38
	v_exp_f32_e32 v225, v39
	v_exp_f32_e32 v224, v40
	v_exp_f32_e32 v226, v41
	v_exp_f32_e32 v211, v42
	v_exp_f32_e32 v212, v43
	v_exp_f32_e32 v213, v44
	v_exp_f32_e32 v215, v45
	v_exp_f32_e32 v214, v46
	v_exp_f32_e32 v216, v47
	v_exp_f32_e32 v217, v48
	v_exp_f32_e32 v218, v67
	s_lshl_b32 s36, s83, 8
	v_pk_fma_f32 v[152:153], v[32:33], s[14:15], v[34:35] op_sel_hi:[1,0,0]
	v_pk_fma_f32 v[156:157], v[30:31], s[14:15], v[34:35] op_sel_hi:[1,0,0]
	v_pk_fma_f32 v[160:161], v[28:29], s[14:15], v[34:35] op_sel_hi:[1,0,0]
	v_pk_fma_f32 v[150:151], v[26:27], s[14:15], v[34:35] op_sel_hi:[1,0,0]
	v_pk_fma_f32 v[154:155], v[24:25], s[14:15], v[34:35] op_sel_hi:[1,0,0]
	v_pk_fma_f32 v[158:159], v[22:23], s[14:15], v[34:35] op_sel_hi:[1,0,0]
	v_pk_fma_f32 v[192:193], v[20:21], s[14:15], v[34:35] op_sel_hi:[1,0,0]
	v_pk_fma_f32 v[194:195], v[18:19], s[14:15], v[34:35] op_sel_hi:[1,0,0]
	s_and_b32 s36, s36, 0xffffc000
	v_mov_b64_e32 v[48:49], v[16:17]
	v_mov_b64_e32 v[32:33], v[16:17]
	v_or_b32_e32 v179, s36, v254
	v_mov_b64_e32 v[46:47], v[14:15]
	v_mov_b64_e32 v[44:45], v[12:13]
	v_mov_b64_e32 v[42:43], v[10:11]
	v_mov_b64_e32 v[40:41], v[8:9]
	v_mov_b64_e32 v[38:39], v[6:7]
	v_mov_b64_e32 v[36:37], v[4:5]
	v_mov_b64_e32 v[34:35], v[2:3]
	v_mov_b64_e32 v[30:31], v[14:15]
	v_mov_b64_e32 v[28:29], v[12:13]
	v_mov_b64_e32 v[26:27], v[10:11]
	v_mov_b64_e32 v[24:25], v[8:9]
	v_mov_b64_e32 v[22:23], v[6:7]
	v_mov_b64_e32 v[20:21], v[4:5]
	v_mov_b64_e32 v[18:19], v[2:3]
	v_add_u32_e32 v146, -8, v179
	global_load_dwordx2 v[146:147], v146, s[68:69]
	v_lshl_add_u64 v[130:131], v[188:189], 0, v[170:171]
	v_lshl_add_u64 v[138:139], v[190:191], 0, v[170:171]
	v_lshl_add_u64 v[134:135], v[130:131], 0, s[100:101]
	v_lshl_add_u64 v[130:131], v[130:131], 0, s[16:17]
	v_lshl_add_u64 v[142:143], v[138:139], 0, s[100:101]
	v_lshl_add_u64 v[138:139], v[138:139], 0, s[16:17]
	global_load_dwordx4 v[130:133], v[130:131], off
	global_load_dwordx4 v[134:137], v[134:135], off
	global_load_dwordx4 v[138:141], v[138:139], off
	global_load_dwordx4 v[142:145], v[142:143], off
	ds_read_b128 v[66:69], v199 offset:49152
	ds_read_b128 v[82:85], v199 offset:57344
	ds_read_b128 v[172:175], v200 offset:49152
	ds_read_b128 v[232:235], v200 offset:57344
	ds_read_b128 v[236:239], v201 offset:49152
	ds_read_b128 v[240:243], v201 offset:57344
	ds_read_b128 v[244:247], v202 offset:49152
	s_branch .Lp5_a1_body
; __device__ __forceinline__ void finishSM(f32x16& p0, f32x16& p1, float alpha, float& l_reg, bf16x8& pa0, bf16x8& pa1, bf16x8& pa2, bf16x8& pa3) {
; #pragma unroll
;     for (int r = 0; r < 16; ++r) p1[r] = __builtin_amdgcn_exp2f(p1[r]);
;     float ps = 0;
; #pragma unroll
;     for (int r = 0; r < 16; ++r) ps += p0[r];
; #pragma unroll
;     for (int r = 0; r < 16; ++r) ps += p1[r];
;     { auto rr = __builtin_amdgcn_permlane32_swap(__float_as_uint(ps), __float_as_uint(ps), false, false);
;       ps = __uint_as_float(rr[0]) + __uint_as_float(rr[1]); }
;     l_reg = l_reg * alpha + ps;
;     ...
;     PK4(p0, 0, pa0); PK4(p0, 8, pa1); PK4(p1, 0, pa2); PK4(p1, 8, pa3);
;     ...
; }
; template <int KB>
; __device__ __forceinline__ void qkt(f32x16& p0, f32x16& p1, const char* K_lds, int r32, int hi, const bf16x8* qr) {
;     p0 = f32x16{}; p1 = f32x16{};
;     const char* kb[4];
; #pragma unroll
;     for (int dd = 0; dd < 4; ++dd) kb[dd] = K_lds + KB * SHM_K + KSWZ(r32, (dd * 16 + hi * 8) * 2);
; #pragma unroll
;     for (int d0 = 0; d0 < 8; ++d0) { const char* a = kb[d0 & 3] + (d0 >> 2) * 128;
;         bf16x8 b0 = *reinterpret_cast<const bf16x8*>(a);
;         bf16x8 b1 = *reinterpret_cast<const bf16x8*>(a + 32 * 256);
;         p0 = __builtin_amdgcn_mfma_f32_32x32x16_bf16(b0, qr[d0], p0, 0, 0, 0);
;         p1 = __builtin_amdgcn_mfma_f32_32x32x16_bf16(b1, qr[d0], p1, 0, 0, 0); }
; }
.LBB0_1299:
	v_add_u32_e32 v146, -8, v179
	global_load_dwordx2 v[146:147], v146, s[68:69]
	v_lshl_add_u64 v[130:131], v[188:189], 0, v[170:171]
	v_lshl_add_u64 v[138:139], v[190:191], 0, v[170:171]
	v_lshl_add_u64 v[134:135], v[130:131], 0, s[100:101]
	v_lshl_add_u64 v[130:131], v[130:131], 0, s[16:17]
	v_lshl_add_u64 v[142:143], v[138:139], 0, s[100:101]
	v_lshl_add_u64 v[138:139], v[138:139], 0, s[16:17]
	global_load_dwordx4 v[130:133], v[130:131], off
	global_load_dwordx4 v[134:137], v[134:135], off
	global_load_dwordx4 v[138:141], v[138:139], off
	global_load_dwordx4 v[142:145], v[142:143], off
	ds_read_b128 v[66:69], v199 offset:49152
	ds_read_b128 v[82:85], v199 offset:57344
	ds_read_b128 v[172:175], v200 offset:49152
	ds_read_b128 v[232:235], v200 offset:57344
	ds_read_b128 v[236:239], v201 offset:49152
	ds_read_b128 v[240:243], v201 offset:57344
	ds_read_b128 v[244:247], v202 offset:49152
	v_exp_f32_e32 v211, v211
	v_exp_f32_e32 v212, v212
	v_exp_f32_e32 v213, v213
	v_exp_f32_e32 v214, v214
	v_exp_f32_e32 v215, v215
	v_exp_f32_e32 v216, v216
	v_exp_f32_e32 v217, v217
	v_exp_f32_e32 v218, v218
	v_exp_f32_e32 v219, v219
	v_exp_f32_e32 v220, v220
	v_exp_f32_e32 v221, v221
	v_exp_f32_e32 v222, v222
	v_exp_f32_e32 v223, v223
	v_exp_f32_e32 v224, v224
	v_exp_f32_e32 v225, v225
	v_exp_f32_e32 v226, v226
.Lp5_a1_body:
	v_exp_f32_e32 v209, v150
	v_add_f32_e32 v150, 0, v219
	v_add_f32_e32 v150, v220, v150
	v_add_f32_e32 v150, v221, v150
	s_waitcnt lgkmcnt(6)
	v_mfma_f32_32x32x16_bf16 v[66:81], v[66:69], v[126:129], 0
	v_add_f32_e32 v150, v222, v150
	v_add_f32_e32 v150, v223, v150
	v_add_f32_e32 v150, v225, v150
	v_add_f32_e32 v150, v224, v150
	v_add_f32_e32 v150, v226, v150
	s_waitcnt lgkmcnt(5)
	v_mfma_f32_32x32x16_bf16 v[82:97], v[82:85], v[126:129], 0
	v_add_f32_e32 v150, v211, v150
	v_add_f32_e32 v150, v212, v150
	v_exp_f32_e32 v194, v194
	s_waitcnt lgkmcnt(4)
	v_mfma_f32_32x32x16_bf16 v[66:81], v[172:175], v[122:125], v[66:81]
	ds_read_b128 v[172:175], v202 offset:57344
	v_exp_f32_e32 v195, v195
	v_exp_f32_e32 v192, v192
	v_exp_f32_e32 v193, v193
	s_waitcnt lgkmcnt(4)
	v_mfma_f32_32x32x16_bf16 v[82:97], v[232:235], v[122:125], v[82:97]
	ds_read_b128 v[232:235], v199 offset:49280
	v_exp_f32_e32 v158, v158
	v_exp_f32_e32 v159, v159
	s_waitcnt lgkmcnt(4)
	v_mfma_f32_32x32x16_bf16 v[66:81], v[236:239], v[118:121], v[66:81]
	ds_read_b128 v[236:239], v199 offset:57472
	v_exp_f32_e32 v207, v154
	v_exp_f32_e32 v208, v155
	v_exp_f32_e32 v210, v151
	s_waitcnt lgkmcnt(4)
	v_mfma_f32_32x32x16_bf16 v[82:97], v[240:243], v[118:121], v[82:97]
	ds_read_b128 v[240:243], v200 offset:49280
	v_exp_f32_e32 v160, v160
	v_exp_f32_e32 v161, v161
	s_waitcnt lgkmcnt(4)
	v_mfma_f32_32x32x16_bf16 v[66:81], v[244:247], v[114:117], v[66:81]
	ds_read_b128 v[244:247], v200 offset:57472
	v_exp_f32_e32 v227, v156
	v_cvt_pk_bf16_f32 v151, v224, v226
	v_cvt_pk_bf16_f32 v154, v214, v216
	v_cvt_pk_bf16_f32 v155, v217, v218
	v_cvt_pk_bf16_f32 v156, v194, v195
	s_waitcnt lgkmcnt(4)
	v_mfma_f32_32x32x16_bf16 v[82:97], v[172:175], v[114:117], v[82:97]
	ds_read_b128 v[172:175], v201 offset:49280
	v_exp_f32_e32 v228, v157
	v_exp_f32_e32 v229, v152
	s_waitcnt lgkmcnt(4)
	v_mfma_f32_32x32x16_bf16 v[66:81], v[232:235], v[110:113], v[66:81]
	ds_read_b128 v[232:235], v201 offset:57472
	v_exp_f32_e32 v230, v153
	v_cvt_pk_bf16_f32 v152, v211, v212
	v_cvt_pk_bf16_f32 v153, v213, v215
	v_cvt_pk_bf16_f32 v157, v192, v193
	v_cvt_pk_bf16_f32 v211, v229, v230
	s_waitcnt lgkmcnt(4)
	v_mfma_f32_32x32x16_bf16 v[82:97], v[236:239], v[110:113], v[82:97]
	ds_read_b128 v[236:239], v202 offset:49280
	v_permlane32_swap_b32_e32 v152, v154
	v_permlane32_swap_b32_e32 v153, v155
	v_add_f32_e32 v249, v213, v150
	v_add_f32_e32 v249, v215, v249
	v_add_f32_e32 v249, v214, v249
	s_waitcnt lgkmcnt(4)
	v_mfma_f32_32x32x16_bf16 v[66:81], v[240:243], v[106:109], v[66:81]
	ds_read_b128 v[240:243], v202 offset:57472
	v_add_f32_e32 v249, v216, v249
	v_add_f32_e32 v249, v217, v249
	v_add_f32_e32 v249, v218, v249
	v_add_f32_e32 v249, v194, v249
	v_add_f32_e32 v248, v195, v249
	s_waitcnt lgkmcnt(4)
	v_mfma_f32_32x32x16_bf16 v[82:97], v[244:247], v[106:109], v[82:97]
	v_add_f32_e32 v248, v192, v248
	v_add_f32_e32 v248, v193, v248
	v_add_f32_e32 v248, v158, v248
	v_add_f32_e32 v248, v159, v248
	v_add_f32_e32 v248, v207, v248
	s_waitcnt lgkmcnt(3)
	v_mfma_f32_32x32x16_bf16 v[66:81], v[172:175], v[102:105], v[66:81]
	v_add_f32_e32 v248, v208, v248
	v_add_f32_e32 v248, v209, v248
	v_add_f32_e32 v248, v210, v248
	v_add_f32_e32 v248, v160, v248
	v_add_f32_e32 v248, v161, v248
	s_waitcnt lgkmcnt(2)
	v_mfma_f32_32x32x16_bf16 v[82:97], v[232:235], v[102:105], v[82:97]
	v_add_f32_e32 v248, v227, v248
	v_add_f32_e32 v248, v228, v248
	v_add_f32_e32 v248, v229, v248
	v_add_f32_e32 v181, v230, v248
	v_mov_b32_e32 v187, v181
	s_waitcnt lgkmcnt(1)
	v_mfma_f32_32x32x16_bf16 v[66:81], v[236:239], v[98:101], v[66:81]
	v_cvt_pk_bf16_f32 v148, v219, v220
	v_cvt_pk_bf16_f32 v149, v221, v222
	v_cvt_pk_bf16_f32 v150, v223, v225
	v_cvt_pk_bf16_f32 v158, v158, v159
	v_cvt_pk_bf16_f32 v159, v207, v208
	s_waitcnt lgkmcnt(0)
; __device__ __forceinline__ void sel_mask_tile(f32x16& p0, f32x16& p1, unsigned wlo, unsigned whi, int hi) {
;     const unsigned NEGB = 0xff800000u;
;     const unsigned lo = wlo >> (4 * hi), h2 = whi >> (4 * hi);
; #pragma unroll
;     for (int r = 0; r < 16; ++r) {
;         const int c = (r & 3) + 8 * (r >> 2);
;         const unsigned m0 = (unsigned)__builtin_amdgcn_sbfe((int)lo, c, 1), m1 = (unsigned)__builtin_amdgcn_sbfe((int)h2, c, 1);
;         p0[r] = __uint_as_float((__float_as_uint(p0[r]) & m0) | (NEGB & ~m0));
;         p1[r] = __uint_as_float((__float_as_uint(p1[r]) & m1) | (NEGB & ~m1));
;     }
; }
; template <int VB>
; __device__ __forceinline__ void pv_tile(f32x16* o, int vb0, bf16x8 pa0, bf16x8 pa1, bf16x8 pa2, bf16x8 pa3) {
;     ...
;     PV_D0(0); PV_D0(1); PV_D0(2); PV_D0(3);
	v_mfma_f32_32x32x16_bf16 v[82:97], v[240:243], v[98:101], v[82:97]
	v_cvt_pk_bf16_f32 v208, v209, v210
	v_cvt_pk_bf16_f32 v210, v227, v228
	v_permlane32_swap_b32_e32 v181, v187
	v_permlane32_swap_b32_e32 v148, v150
	v_permlane32_swap_b32_e32 v149, v151
	v_cvt_pk_bf16_f32 v209, v160, v161
	v_permlane32_swap_b32_e32 v208, v210
	v_permlane32_swap_b32_e32 v156, v158
	v_permlane32_swap_b32_e32 v157, v159
	v_permlane32_swap_b32_e32 v209, v211
	v_lshl_add_u64 v[194:195], v[188:189], 0, v[170:171]
	v_lshl_add_u64 v[192:193], v[190:191], 0, v[170:171]
	ds_read_b64_tr_b16 v[172:173], v1 offset:0x0
	ds_read_b64_tr_b16 v[174:175], v1 offset:0x800
	ds_read_b64_tr_b16 v[212:213], v1 offset:0x200
	ds_read_b64_tr_b16 v[214:215], v1 offset:0xa00
	ds_read_b64_tr_b16 v[216:217], v1 offset:0x400
	ds_read_b64_tr_b16 v[218:219], v1 offset:0xc00
	ds_read_b64_tr_b16 v[220:221], v1 offset:0x600
	ds_read_b64_tr_b16 v[222:223], v1 offset:0xe00
	ds_read_b64_tr_b16 v[224:225], v1 offset:0x1000
	ds_read_b64_tr_b16 v[226:227], v1 offset:0x1800
	ds_read_b64_tr_b16 v[232:233], v1 offset:0x1200
	ds_read_b64_tr_b16 v[234:235], v1 offset:0x1a00
	ds_read_b64_tr_b16 v[236:237], v1 offset:0x1400
	ds_read_b64_tr_b16 v[238:239], v1 offset:0x1c00
	s_nop 0
	s_waitcnt lgkmcnt(12)
	v_mfma_f32_32x32x16_bf16 v[2:17], v[148:151], v[172:175], v[2:17]
	ds_read_b64_tr_b16 v[240:241], v1 offset:0x1600
	ds_read_b64_tr_b16 v[242:243], v1 offset:0x1e00
	s_waitcnt vmcnt(4)
	v_lshrrev_b32_e32 v160, v163, v146
	v_lshrrev_b32_e32 v161, v163, v147
	v_bfe_i32 v146, v160, 0, 1
	v_bfe_i32 v147, v161, 0, 1
	v_bitop3_b32 v146, v66, s74, v146 bitop3:0xe4
	v_bitop3_b32 v66, v82, s74, v147 bitop3:0xe4
	s_waitcnt lgkmcnt(12)
	v_mfma_f32_32x32x16_bf16 v[50:65], v[148:151], v[212:215], v[50:65]
	ds_read_b64_tr_b16 v[244:245], v1 offset:0x2000
	ds_read_b64_tr_b16 v[246:247], v1 offset:0x2800
	v_bfe_i32 v82, v160, 1, 1
	v_bfe_i32 v147, v161, 1, 1
	v_bitop3_b32 v82, v67, s74, v82 bitop3:0xe4
	v_bitop3_b32 v67, v83, s74, v147 bitop3:0xe4
	v_bfe_i32 v83, v160, 2, 1
	v_bfe_i32 v147, v161, 2, 1
	s_waitcnt lgkmcnt(12)
	v_mfma_f32_32x32x16_bf16 v[34:49], v[148:151], v[216:219], v[34:49]
	ds_read_b64_tr_b16 v[248:249], v1 offset:0x2200
	ds_read_b64_tr_b16 v[250:251], v1 offset:0x2a00
	v_bitop3_b32 v83, v68, s74, v83 bitop3:0xe4
	v_bitop3_b32 v68, v84, s74, v147 bitop3:0xe4
	v_bfe_i32 v84, v160, 3, 1
	s_waitcnt lgkmcnt(12)
	v_mfma_f32_32x32x16_bf16 v[18:33], v[148:151], v[220:223], v[18:33]
	ds_read_b64_tr_b16 v[220:221], v1 offset:0x2400
	ds_read_b64_tr_b16 v[222:223], v1 offset:0x2c00
	v_bfe_i32 v148, v161, 3, 1
	v_bitop3_b32 v147, v69, s74, v84 bitop3:0xe4
	v_bfe_i32 v84, v160, 8, 1
	v_bitop3_b32 v69, v85, s74, v148 bitop3:0xe4
	v_bfe_i32 v85, v161, 8, 1
	v_bitop3_b32 v148, v70, s74, v84 bitop3:0xe4
	v_bfe_i32 v84, v160, 9, 1
	s_waitcnt lgkmcnt(12)
	v_mfma_f32_32x32x16_bf16 v[2:17], v[152:155], v[224:227], v[2:17]
	ds_read_b64_tr_b16 v[224:225], v1 offset:0x2600
	ds_read_b64_tr_b16 v[226:227], v1 offset:0x2e00
	v_bitop3_b32 v70, v86, s74, v85 bitop3:0xe4
	v_bfe_i32 v85, v161, 9, 1
	v_bitop3_b32 v149, v71, s74, v84 bitop3:0xe4
	v_bfe_i32 v84, v160, 10, 1
	v_bitop3_b32 v71, v87, s74, v85 bitop3:0xe4
	v_bfe_i32 v85, v161, 10, 1
	s_waitcnt lgkmcnt(12)
	v_mfma_f32_32x32x16_bf16 v[50:65], v[152:155], v[232:235], v[50:65]
	ds_read_b64_tr_b16 v[232:233], v1 offset:0x3000
	ds_read_b64_tr_b16 v[234:235], v1 offset:0x3800
	v_bitop3_b32 v87, v72, s74, v84 bitop3:0xe4
	v_bfe_i32 v84, v160, 11, 1
	v_bitop3_b32 v72, v88, s74, v85 bitop3:0xe4
	v_bfe_i32 v85, v161, 11, 1
	v_bitop3_b32 v88, v73, s74, v84 bitop3:0xe4
	v_bfe_i32 v73, v160, 16, 1
	v_bitop3_b32 v84, v89, s74, v85 bitop3:0xe4
	s_waitcnt lgkmcnt(12)
	v_mfma_f32_32x32x16_bf16 v[34:49], v[152:155], v[236:239], v[34:49]
	ds_read_b64_tr_b16 v[236:237], v1 offset:0x3200
	ds_read_b64_tr_b16 v[238:239], v1 offset:0x3a00
	v_bfe_i32 v85, v161, 16, 1
	v_bitop3_b32 v89, v74, s74, v73 bitop3:0xe4
	v_bfe_i32 v73, v160, 17, 1
	v_bfe_i32 v74, v161, 17, 1
	v_bitop3_b32 v85, v90, s74, v85 bitop3:0xe4
	v_bitop3_b32 v90, v75, s74, v73 bitop3:0xe4
	s_waitcnt lgkmcnt(12)
	v_mfma_f32_32x32x16_bf16 v[18:33], v[152:155], v[240:243], v[18:33]
	ds_read_b64_tr_b16 v[240:241], v1 offset:0x3400
	ds_read_b64_tr_b16 v[242:243], v1 offset:0x3c00
	v_bitop3_b32 v86, v91, s74, v74 bitop3:0xe4
	v_bfe_i32 v73, v160, 18, 1
	v_bfe_i32 v74, v161, 18, 1
	v_bitop3_b32 v91, v76, s74, v73 bitop3:0xe4
	v_bitop3_b32 v76, v92, s74, v74 bitop3:0xe4
	v_bfe_i32 v73, v160, 19, 1
	v_bfe_i32 v74, v161, 19, 1
	s_waitcnt lgkmcnt(12)
	v_mfma_f32_32x32x16_bf16 v[2:17], v[156:159], v[244:247], v[2:17]
	ds_read_b64_tr_b16 v[244:245], v1 offset:0x3600
	ds_read_b64_tr_b16 v[246:247], v1 offset:0x3e00
	v_bitop3_b32 v92, v77, s74, v73 bitop3:0xe4
	v_bitop3_b32 v77, v93, s74, v74 bitop3:0xe4
	v_bfe_i32 v73, v160, 24, 1
	v_bfe_i32 v74, v161, 24, 1
	v_bitop3_b32 v93, v78, s74, v73 bitop3:0xe4
	v_bitop3_b32 v78, v94, s74, v74 bitop3:0xe4
	s_waitcnt lgkmcnt(12)
	v_mfma_f32_32x32x16_bf16 v[50:65], v[156:159], v[248:251], v[50:65]
	v_bfe_i32 v73, v160, 25, 1
	v_bfe_i32 v74, v161, 25, 1
	v_bitop3_b32 v79, v79, s74, v73 bitop3:0xe4
	v_bitop3_b32 v73, v95, s74, v74 bitop3:0xe4
	v_bfe_i32 v74, v160, 26, 1
	v_bfe_i32 v75, v161, 26, 1
	v_bitop3_b32 v80, v80, s74, v74 bitop3:0xe4
	s_waitcnt lgkmcnt(10)
	v_mfma_f32_32x32x16_bf16 v[34:49], v[156:159], v[220:223], v[34:49]
	v_bitop3_b32 v74, v96, s74, v75 bitop3:0xe4
	v_bfe_i32 v75, v160, 27, 1
	v_bfe_i32 v94, v161, 27, 1
	v_bitop3_b32 v81, v81, s74, v75 bitop3:0xe4
	v_bitop3_b32 v75, v97, s74, v94 bitop3:0xe4
	v_max_f32_e32 v94, v82, v82
	s_waitcnt lgkmcnt(8)
; __device__ __forceinline__ void partialSM(f32x16& p0, f32x16& p1, float& m_reg, float& mn, float& alpha) {
;     ...
; #pragma unroll
;     for (int r = 0; r < 16; ++r) pmax = fmaxf(pmax, p1[r]);
;     { auto rr = __builtin_amdgcn_permlane32_swap(__float_as_uint(pmax), __float_as_uint(pmax), false, false);
;       pmax = fmaxf(__uint_as_float(rr[0]), __uint_as_float(rr[1])); }
;     constexpr float C2 = 1.4426950408889634f * SCALE;
;     if (__builtin_expect(__all((pmax - m_reg) * SCALE <= THR), 1)) { mn = m_reg; alpha = 1.f; }
;     else { mn = fmaxf(m_reg, pmax); alpha = __builtin_amdgcn_exp2f((m_reg - mn) * C2); m_reg = mn; }
;     const float mnL = -mn * C2;
; #pragma unroll
;     for (int r = 0; r < 16; ++r) p0[r] = fmaf(p0[r], C2, mnL);
; #pragma unroll
;     for (int r = 0; r < 16; ++r) p1[r] = fmaf(p1[r], C2, mnL);
	v_mfma_f32_32x32x16_bf16 v[18:33], v[156:159], v[224:227], v[18:33]
	v_max_f32_e32 v95, v146, v146
	v_max_f32_e32 v94, v95, v94
	v_max3_f32 v94, v94, v83, v147
	v_max3_f32 v94, v94, v148, v149
	v_max3_f32 v94, v94, v87, v88
	v_max3_f32 v94, v94, v89, v90
	v_max3_f32 v94, v94, v91, v92
	s_waitcnt lgkmcnt(6)
	v_mfma_f32_32x32x16_bf16 v[2:17], v[208:211], v[232:235], v[2:17]
	v_max3_f32 v94, v94, v93, v79
	v_max3_f32 v94, v94, v80, v81
	v_max3_f32 v94, v94, v66, v67
	v_max3_f32 v94, v94, v68, v69
	v_max3_f32 v94, v94, v70, v71
	v_max3_f32 v94, v94, v72, v84
	s_waitcnt lgkmcnt(4)
	v_mfma_f32_32x32x16_bf16 v[50:65], v[208:211], v[236:239], v[50:65]
	v_max3_f32 v94, v94, v85, v86
	v_max3_f32 v94, v94, v76, v77
	v_max3_f32 v94, v94, v78, v73
	v_max3_f32 v94, v94, v74, v75
	v_mov_b32_e32 v95, v94
	s_nop 1
	v_permlane32_swap_b32_e32 v94, v95
	s_waitcnt lgkmcnt(2)
	v_mfma_f32_32x32x16_bf16 v[34:49], v[208:211], v[240:243], v[34:49]
	v_max_f32_e32 v95, v95, v95
	v_max_f32_e32 v94, v94, v94
	v_max_f32_e32 v94, v94, v95
	v_max_f32_e32 v96, v206, v206
	v_sub_f32_e32 v95, v94, v206
	v_max_f32_e32 v94, v96, v94
	v_sub_f32_e32 v96, v206, v94
	s_waitcnt lgkmcnt(0)
	v_mfma_f32_32x32x16_bf16 v[18:33], v[208:211], v[244:247], v[18:33]
	s_waitcnt vmcnt(0)
	ds_write_b128 v204, v[138:141] offset:32768
	ds_write_b128 v204, v[142:145] offset:40960
	v_mul_f32_e32 v96, 0x3e0293ee, v96
	v_mul_f32_e32 v95, 0x3db504f3, v95
	v_exp_f32_e32 v96, v96
	v_cmp_ge_f32_e32 vcc, s75, v95
	s_cmp_eq_u64 vcc, exec
	s_cselect_b64 s[6:7], -1, 0
	s_barrier
	s_waitcnt vmcnt(0)
	v_cndmask_b32_e64 v208, v96, 1.0, s[6:7]
	v_cmp_gt_f32_e32 vcc, 1.0, v208
	ds_write_b128 v197, v[130:133]
	ds_write_b128 v198, v[134:137]
	s_cbranch_vccz .LBB0_1303
	s_and_saveexec_b64 s[36:37], s[0:1]
	ds_write_b32 v185, v208 offset:128
	s_or_b64 exec, exec, s[36:37]
	s_waitcnt lgkmcnt(0)
	ds_read_b128 v[150:153], v183 offset:224
	ds_read_b128 v[154:157], v183 offset:192
	ds_read_b128 v[158:161], v183 offset:160
	ds_read_b128 v[172:175], v183 offset:128
	s_waitcnt lgkmcnt(3)
	v_pk_mul_f32 v[16:17], v[16:17], v[152:153]
	s_waitcnt lgkmcnt(2)
	v_pk_mul_f32 v[12:13], v[12:13], v[156:157]
	s_waitcnt lgkmcnt(1)
	v_pk_mul_f32 v[8:9], v[8:9], v[160:161]
	s_waitcnt lgkmcnt(0)
	v_pk_mul_f32 v[4:5], v[4:5], v[174:175]
	v_pk_mul_f32 v[14:15], v[14:15], v[150:151]
	v_pk_mul_f32 v[10:11], v[10:11], v[154:155]
	v_pk_mul_f32 v[6:7], v[6:7], v[158:159]
	v_pk_mul_f32 v[2:3], v[2:3], v[172:173]
	v_pk_mul_f32 v[64:65], v[64:65], v[152:153]
	v_pk_mul_f32 v[60:61], v[60:61], v[156:157]
	v_pk_mul_f32 v[56:57], v[56:57], v[160:161]
	v_pk_mul_f32 v[52:53], v[52:53], v[174:175]
	v_pk_mul_f32 v[62:63], v[62:63], v[150:151]
	v_pk_mul_f32 v[58:59], v[58:59], v[154:155]
	v_pk_mul_f32 v[54:55], v[54:55], v[158:159]
	v_pk_mul_f32 v[50:51], v[50:51], v[172:173]
	v_pk_mul_f32 v[48:49], v[48:49], v[152:153]
	v_pk_mul_f32 v[44:45], v[44:45], v[156:157]
	v_pk_mul_f32 v[40:41], v[40:41], v[160:161]
	v_pk_mul_f32 v[36:37], v[36:37], v[174:175]
	v_pk_mul_f32 v[46:47], v[46:47], v[150:151]
	v_pk_mul_f32 v[42:43], v[42:43], v[154:155]
	v_pk_mul_f32 v[38:39], v[38:39], v[158:159]
	v_pk_mul_f32 v[34:35], v[34:35], v[172:173]
	v_pk_mul_f32 v[32:33], v[32:33], v[152:153]
	v_pk_mul_f32 v[28:29], v[28:29], v[156:157]
	v_pk_mul_f32 v[24:25], v[24:25], v[160:161]
	v_pk_mul_f32 v[20:21], v[20:21], v[174:175]
	v_pk_mul_f32 v[30:31], v[30:31], v[150:151]
	v_pk_mul_f32 v[26:27], v[26:27], v[154:155]
	v_pk_mul_f32 v[22:23], v[22:23], v[158:159]
	v_pk_mul_f32 v[18:19], v[18:19], v[172:173]
.LBB0_1303:
	v_cndmask_b32_e64 v206, v94, v206, s[6:7]
	v_mul_f32_e32 v207, 0xbe0293ee, v206
	v_fmamk_f32 v146, v146, 0x3e0293ee, v207
	v_fmamk_f32 v159, v147, 0x3e0293ee, v207
	v_fmamk_f32 v147, v82, 0x3e0293ee, v207
	v_fmamk_f32 v160, v148, 0x3e0293ee, v207
	v_fmamk_f32 v148, v83, 0x3e0293ee, v207
	v_fmamk_f32 v161, v149, 0x3e0293ee, v207
	v_fmamk_f32 v149, v87, 0x3e0293ee, v207
	v_fmamk_f32 v158, v88, 0x3e0293ee, v207
	v_fmamk_f32 v150, v89, 0x3e0293ee, v207
	v_fmamk_f32 v151, v90, 0x3e0293ee, v207
	v_fmamk_f32 v155, v91, 0x3e0293ee, v207
	v_fmamk_f32 v157, v92, 0x3e0293ee, v207
	v_fmamk_f32 v152, v93, 0x3e0293ee, v207
	v_fmamk_f32 v153, v79, 0x3e0293ee, v207
	v_fmamk_f32 v154, v80, 0x3e0293ee, v207
	v_fmamk_f32 v156, v81, 0x3e0293ee, v207
	v_fmamk_f32 v210, v71, 0x3e0293ee, v207
	v_fmamk_f32 v209, v78, 0x3e0293ee, v207
	v_fmamk_f32 v217, v66, 0x3e0293ee, v207
	v_fmamk_f32 v218, v67, 0x3e0293ee, v207
	v_fmamk_f32 v219, v68, 0x3e0293ee, v207
	v_fmamk_f32 v220, v69, 0x3e0293ee, v207
	v_fmamk_f32 v221, v70, 0x3e0293ee, v207
	v_fmamk_f32 v211, v72, 0x3e0293ee, v207
	v_fmamk_f32 v212, v84, 0x3e0293ee, v207
	v_fmamk_f32 v213, v85, 0x3e0293ee, v207
	v_fmamk_f32 v214, v86, 0x3e0293ee, v207
	v_fmamk_f32 v215, v76, 0x3e0293ee, v207
	v_fmamk_f32 v216, v77, 0x3e0293ee, v207
	v_fmamk_f32 v222, v73, 0x3e0293ee, v207
	v_fmamk_f32 v223, v74, 0x3e0293ee, v207
	v_fmac_f32_e32 v207, 0x3e0293ee, v75
	s_waitcnt lgkmcnt(0)
	s_barrier
	global_load_dwordx2 v[228:229], v179, s[68:69]
	s_add_i32 s98, s82, 2
	s_cmp_gt_u32 s98, s81
	s_cbranch_scc1 .Lp5_a2
	v_add_co_u32_e32 v130, vcc, 0x60000, v194
	s_nop 1
	v_addc_co_u32_e32 v131, vcc, 0, v195, vcc
	v_add_co_u32_e32 v134, vcc, 0x70000, v194
	s_nop 1
	v_addc_co_u32_e32 v135, vcc, 0, v195, vcc
	v_add_co_u32_e32 v138, vcc, 0x60000, v192
	global_load_dwordx4 v[130:133], v[130:131], off
	s_nop 0
	global_load_dwordx4 v[134:137], v[134:135], off
	v_addc_co_u32_e32 v139, vcc, 0, v193, vcc
	v_add_co_u32_e32 v142, vcc, 0x70000, v192
	s_nop 1
	v_addc_co_u32_e32 v143, vcc, 0, v193, vcc
	global_load_dwordx4 v[138:141], v[138:139], off
	s_nop 0
	global_load_dwordx4 v[142:145], v[142:143], off
; __device__ __forceinline__ void finishSM(f32x16& p0, f32x16& p1, float alpha, float& l_reg, bf16x8& pa0, bf16x8& pa1, bf16x8& pa2, bf16x8& pa3) {
; #pragma unroll
;     for (int r = 0; r < 16; ++r) p1[r] = __builtin_amdgcn_exp2f(p1[r]);
;     float ps = 0;
; #pragma unroll
;     for (int r = 0; r < 16; ++r) ps += p0[r];
; #pragma unroll
;     for (int r = 0; r < 16; ++r) ps += p1[r];
;     { auto rr = __builtin_amdgcn_permlane32_swap(__float_as_uint(ps), __float_as_uint(ps), false, false);
;       ps = __uint_as_float(rr[0]) + __uint_as_float(rr[1]); }
;     l_reg = l_reg * alpha + ps;
;     ...
;     PK4(p0, 0, pa0); PK4(p0, 8, pa1); PK4(p1, 0, pa2); PK4(p1, 8, pa3);
;     ...
; }
; template <int KB>
; __device__ __forceinline__ void qkt(f32x16& p0, f32x16& p1, const char* K_lds, int r32, int hi, const bf16x8* qr) {
;     p0 = f32x16{}; p1 = f32x16{};
;     const char* kb[4];
; #pragma unroll
;     for (int dd = 0; dd < 4; ++dd) kb[dd] = K_lds + KB * SHM_K + KSWZ(r32, (dd * 16 + hi * 8) * 2);
; #pragma unroll
;     for (int d0 = 0; d0 < 8; ++d0) { const char* a = kb[d0 & 3] + (d0 >> 2) * 128;
;         bf16x8 b0 = *reinterpret_cast<const bf16x8*>(a);
;         bf16x8 b1 = *reinterpret_cast<const bf16x8*>(a + 32 * 256);
;         p0 = __builtin_amdgcn_mfma_f32_32x32x16_bf16(b0, qr[d0], p0, 0, 0, 0);
;         p1 = __builtin_amdgcn_mfma_f32_32x32x16_bf16(b1, qr[d0], p1, 0, 0, 0); }
; }
.Lp5_a2:
	ds_read_b128 v[66:69], v199 offset:32768
	ds_read_b128 v[70:73], v199 offset:40960
	ds_read_b128 v[172:175], v200 offset:32768
	ds_read_b128 v[224:227], v200 offset:40960
	ds_read_b128 v[232:235], v201 offset:32768
	ds_read_b128 v[236:239], v201 offset:40960
	ds_read_b128 v[240:243], v202 offset:32768
	ds_read_b128 v[244:247], v202 offset:40960
	v_exp_f32_e32 v146, v146
	v_exp_f32_e32 v147, v147
	v_exp_f32_e32 v148, v148
	v_exp_f32_e32 v149, v149
	v_exp_f32_e32 v150, v150
	v_exp_f32_e32 v151, v151
	v_exp_f32_e32 v152, v152
	v_exp_f32_e32 v153, v153
	v_exp_f32_e32 v154, v154
	v_exp_f32_e32 v155, v155
	v_exp_f32_e32 v156, v156
	v_exp_f32_e32 v157, v157
	v_exp_f32_e32 v158, v158
	v_exp_f32_e32 v159, v159
	v_exp_f32_e32 v160, v160
	v_exp_f32_e32 v161, v161
	v_exp_f32_e32 v211, v211
	v_exp_f32_e32 v212, v212
	s_waitcnt lgkmcnt(7)
	v_mfma_f32_32x32x16_bf16 v[82:97], v[66:69], v[126:129], 0
	v_exp_f32_e32 v213, v213
	v_exp_f32_e32 v214, v214
	v_exp_f32_e32 v215, v215
	s_waitcnt lgkmcnt(6)
	v_mfma_f32_32x32x16_bf16 v[66:81], v[70:73], v[126:129], 0
	v_exp_f32_e32 v216, v216
	v_exp_f32_e32 v207, v207
	s_waitcnt lgkmcnt(5)
	v_mfma_f32_32x32x16_bf16 v[82:97], v[172:175], v[122:125], v[82:97]
	ds_read_b128 v[172:175], v199 offset:32896
	v_exp_f32_e32 v250, v219
	v_exp_f32_e32 v219, v209
	v_add_f32_e32 v209, 0, v146
	v_add_f32_e32 v209, v147, v209
	s_waitcnt lgkmcnt(5)
	v_mfma_f32_32x32x16_bf16 v[66:81], v[224:227], v[122:125], v[66:81]
	ds_read_b128 v[224:227], v199 offset:41088
	v_add_f32_e32 v209, v148, v209
	v_add_f32_e32 v209, v159, v209
	v_add_f32_e32 v209, v160, v209
	v_add_f32_e32 v209, v161, v209
	v_add_f32_e32 v209, v149, v209
	s_waitcnt lgkmcnt(5)
	v_mfma_f32_32x32x16_bf16 v[82:97], v[232:235], v[118:121], v[82:97]
	ds_read_b128 v[232:235], v200 offset:32896
	v_add_f32_e32 v209, v158, v209
	v_add_f32_e32 v209, v150, v209
	v_add_f32_e32 v209, v151, v209
	v_add_f32_e32 v209, v155, v209
	v_add_f32_e32 v209, v157, v209
	s_waitcnt lgkmcnt(5)
	v_mfma_f32_32x32x16_bf16 v[66:81], v[236:239], v[118:121], v[66:81]
	ds_read_b128 v[236:239], v200 offset:41088
	v_exp_f32_e32 v248, v217
	v_add_f32_e32 v209, v152, v209
	v_exp_f32_e32 v249, v218
	s_waitcnt lgkmcnt(5)
	v_mfma_f32_32x32x16_bf16 v[82:97], v[240:243], v[114:117], v[82:97]
	ds_read_b128 v[240:243], v201 offset:32896
	v_add_f32_e32 v209, v153, v209
	v_add_f32_e32 v209, v154, v209
	v_exp_f32_e32 v251, v220
	v_add_f32_e32 v209, v156, v209
	s_waitcnt lgkmcnt(5)
	v_mfma_f32_32x32x16_bf16 v[66:81], v[244:247], v[114:117], v[66:81]
	ds_read_b128 v[244:247], v201 offset:41088
	v_exp_f32_e32 v217, v221
	v_add_f32_e32 v209, v248, v209
	v_exp_f32_e32 v218, v210
	s_waitcnt lgkmcnt(5)
	v_mfma_f32_32x32x16_bf16 v[82:97], v[172:175], v[110:113], v[82:97]
	ds_read_b128 v[172:175], v202 offset:32896
	v_add_f32_e32 v209, v249, v209
	v_add_f32_e32 v209, v250, v209
	v_add_f32_e32 v209, v251, v209
	v_add_f32_e32 v209, v217, v209
	v_add_f32_e32 v209, v218, v209
	s_waitcnt lgkmcnt(5)
	v_mfma_f32_32x32x16_bf16 v[66:81], v[224:227], v[110:113], v[66:81]
	ds_read_b128 v[224:227], v202 offset:41088
	v_add_f32_e32 v209, v211, v209
	v_add_f32_e32 v209, v212, v209
	v_add_f32_e32 v209, v213, v209
	v_exp_f32_e32 v220, v222
	s_waitcnt lgkmcnt(5)
	v_mfma_f32_32x32x16_bf16 v[82:97], v[232:235], v[106:109], v[82:97]
	v_add_f32_e32 v209, v214, v209
	v_exp_f32_e32 v221, v223
	v_add_f32_e32 v209, v215, v209
	v_add_f32_e32 v209, v216, v209
	s_waitcnt lgkmcnt(4)
	v_mfma_f32_32x32x16_bf16 v[66:81], v[236:239], v[106:109], v[66:81]
	v_add_f32_e32 v209, v219, v209
	v_add_f32_e32 v209, v220, v209
	v_add_f32_e32 v209, v221, v209
	v_add_f32_e32 v209, v207, v209
	v_mov_b32_e32 v210, v209
	s_waitcnt lgkmcnt(3)
	v_mfma_f32_32x32x16_bf16 v[82:97], v[240:243], v[102:105], v[82:97]
	v_cvt_pk_bf16_f32 v146, v146, v147
	v_cvt_pk_bf16_f32 v147, v148, v159
	v_cvt_pk_bf16_f32 v148, v160, v161
	v_cvt_pk_bf16_f32 v149, v149, v158
	v_cvt_pk_bf16_f32 v150, v150, v151
	s_waitcnt lgkmcnt(2)
	v_mfma_f32_32x32x16_bf16 v[66:81], v[244:247], v[102:105], v[66:81]
	v_cvt_pk_bf16_f32 v151, v155, v157
	v_cvt_pk_bf16_f32 v152, v152, v153
	v_cvt_pk_bf16_f32 v153, v154, v156
	v_cvt_pk_bf16_f32 v154, v248, v249
	v_cvt_pk_bf16_f32 v155, v250, v251
	s_waitcnt lgkmcnt(1)
	v_mfma_f32_32x32x16_bf16 v[82:97], v[172:175], v[98:101], v[82:97]
	v_cvt_pk_bf16_f32 v156, v217, v218
	v_cvt_pk_bf16_f32 v157, v211, v212
	v_cvt_pk_bf16_f32 v158, v213, v214
	v_cvt_pk_bf16_f32 v159, v215, v216
	v_cvt_pk_bf16_f32 v160, v219, v220
	s_waitcnt lgkmcnt(0)
	v_mfma_f32_32x32x16_bf16 v[66:81], v[224:227], v[98:101], v[66:81]
	v_cvt_pk_bf16_f32 v161, v221, v207
	v_permlane32_swap_b32_e32 v209, v210
	v_permlane32_swap_b32_e32 v146, v148
	v_permlane32_swap_b32_e32 v147, v149
	v_permlane32_swap_b32_e32 v150, v152
	v_permlane32_swap_b32_e32 v151, v153
	v_permlane32_swap_b32_e32 v154, v156
	v_permlane32_swap_b32_e32 v155, v157
	v_permlane32_swap_b32_e32 v158, v160
	v_permlane32_swap_b32_e32 v159, v161
	s_add_i32 s82, s82, 2
	s_cmp_le_u32 s82, s81
	s_cselect_b64 s[36:37], -1, 0
	s_cmp_gt_u32 s82, s81
	s_cbranch_scc1 .Lp5_skip_ld

; __device__ __forceinline__ void partialSM(f32x16& p0, f32x16& p1, float& m_reg, float& mn, float& alpha) {
;     ...
;     if (__builtin_expect(__all((pmax - m_reg) * SCALE <= THR), 1)) { mn = m_reg; alpha = 1.f; }
;     else { mn = fmaxf(m_reg, pmax); alpha = __builtin_amdgcn_exp2f((m_reg - mn) * C2); m_reg = mn; }
;     const float mnL = -mn * C2;
; #pragma unroll
;     for (int r = 0; r < 16; ++r) p0[r] = fmaf(p0[r], C2, mnL);
; #pragma unroll
;     for (int r = 0; r < 16; ++r) p1[r] = fmaf(p1[r], C2, mnL);
; __device__ __forceinline__ void attn_block(const BlockRef& cur, const BlockRef& nxt, char* lds, Seam& S) {
;     ...
;     for (int t = 1; t + 1 < NT; t += 2) {
;         HALF_STEP(pB0, pB1, mnB, alB, pA0, pA1, alA, t, 1, 0, 0);
;         HALF_STEP(pA0, pA1, mnA, alA, pB0, pB1, alB, t + 1, 0, 1, 1);
;     }
.LBB0_1311:
	v_cndmask_b32_e64 v206, v76, v206, s[6:7]
	v_mul_f32_e32 v76, 0xbe0293ee, v206
	v_mov_b32_e32 v218, v76
	v_fmamk_f32 v219, v192, 0x3e0293ee, v76
	v_fmamk_f32 v220, v146, 0x3e0293ee, v76
	v_fmamk_f32 v221, v147, 0x3e0293ee, v76
	v_fmamk_f32 v222, v148, 0x3e0293ee, v76
	v_fmamk_f32 v223, v149, 0x3e0293ee, v76
	v_fmamk_f32 v225, v150, 0x3e0293ee, v76
	v_fmamk_f32 v224, v88, 0x3e0293ee, v76
	v_fmamk_f32 v226, v89, 0x3e0293ee, v76
	v_fmamk_f32 v211, v90, 0x3e0293ee, v76
	v_fmamk_f32 v212, v91, 0x3e0293ee, v76
	v_fmamk_f32 v213, v92, 0x3e0293ee, v76
	v_fmamk_f32 v215, v93, 0x3e0293ee, v76
	v_fmamk_f32 v214, v94, 0x3e0293ee, v76
	v_fmamk_f32 v216, v95, 0x3e0293ee, v76
	v_fmamk_f32 v217, v96, 0x3e0293ee, v76
	v_fmac_f32_e32 v218, 0x3e0293ee, v97
	v_pk_fma_f32 v[194:195], v[66:67], s[14:15], v[76:77] op_sel_hi:[1,0,0]
	v_add_f32_e32 v66, v181, v187
	v_fmac_f32_e32 v66, v177, v205
	v_add_f32_e32 v205, v209, v210
	v_pk_fma_f32 v[192:193], v[82:83], s[14:15], v[76:77] op_sel_hi:[1,0,0]
	v_pk_fma_f32 v[158:159], v[84:85], s[14:15], v[76:77] op_sel_hi:[1,0,0]
	v_pk_fma_f32 v[154:155], v[86:87], s[14:15], v[76:77] op_sel_hi:[1,0,0]
	v_pk_fma_f32 v[150:151], v[74:75], s[14:15], v[76:77] op_sel_hi:[1,0,0]
	v_pk_fma_f32 v[160:161], v[68:69], s[14:15], v[76:77] op_sel_hi:[1,0,0]
	v_pk_fma_f32 v[156:157], v[70:71], s[14:15], v[76:77] op_sel_hi:[1,0,0]
	v_pk_fma_f32 v[152:153], v[72:73], s[14:15], v[76:77] op_sel_hi:[1,0,0]
	v_fmac_f32_e32 v205, v66, v208
	v_add_u32_e32 v179, 16, v179
	v_lshl_add_u64 v[188:189], v[188:189], 0, s[16:17]
	s_cmp_ge_u32 s82, s81
	v_lshl_add_u64 v[190:191], v[190:191], 0, s[16:17]
	s_waitcnt lgkmcnt(0)
	s_barrier
	s_cbranch_scc1 .LBB0_1313
	v_mov_b32_e32 v177, v207
	s_branch .LBB0_1299

; #define SBAR() __builtin_amdgcn_sched_barrier(0)
; #define SLOAD_H(Kp, Vp, k0) do { S.st_v0 = load8(ROW(Vp, k0, sr)); S.st_v1 = load8(ROW(Vp, k0, 32 + sr));              \
;                          S.st_k0 = load8(ROW(Kp, k0, sr)); S.st_k1 = load8(ROW(Kp, k0, 32 + sr)); } while (0)
; #define RESC(a) do { if (__any((a) < 1.f)) { if (hi == 0) al_l[r32] = (a); asm volatile("s_waitcnt lgkmcnt(0)" ::: "memory");              \
;                      for (int d_ = 0; d_ < 4; ++d_) for (int r = 0; r < 16; ++r) o[d_][r] *= al_l[crow(r, hi)]; } } while (0)
; #define MASKT(P0_, P1_) sel_mask_tile(P0_, P1_, mw.x, mw.y, hi)
; __device__ __forceinline__ void attn_block(const BlockRef& cur, const BlockRef& nxt, char* lds, Seam& S) {
;     ...
;     mw = LDMASK(NT - 1);
;     SBAR(); qkt<1>(pB0, pB1, K_lds, r32, hi, S.qr); SBAR();
;     SLOAD_H(nxt.K, nxt.V, 0); SBAR();
; #pragma unroll
;     for (int d0 = 0; d0 < 8; ++d0) S.qr[d0] = load8(nxt.Q + (size_t)(wid * QBLK + r32) * LD + d0 * 16 + hi * 8);
;     SBAR();
;     finishSM(pA0, pA1, alA, l_reg, pa0, pa1, pa2, pa3); SBAR();
;     pv_tile<0>(o, vb0, pa0, pa1, pa2, pa3);
;     MASKT(pB0, pB1); partialSM(pB0, pB1, m_reg, mnB, alB); __syncthreads(); RESC(alB);
.LBB0_1313:
	v_exp_f32_e32 v211, v211
	v_exp_f32_e32 v212, v212
	v_exp_f32_e32 v213, v213
	v_exp_f32_e32 v214, v214
	v_exp_f32_e32 v215, v215
	v_exp_f32_e32 v216, v216
	v_exp_f32_e32 v217, v217
	v_exp_f32_e32 v218, v218
	v_exp_f32_e32 v219, v219
	v_exp_f32_e32 v220, v220
	v_exp_f32_e32 v221, v221
	v_exp_f32_e32 v222, v222
	v_exp_f32_e32 v223, v223
	v_exp_f32_e32 v224, v224
	v_exp_f32_e32 v225, v225
	v_exp_f32_e32 v226, v226
	v_lshl_add_u32 v66, s81, 3, v165
	global_load_dwordx2 v[188:189], v66, s[68:69]
	ds_read_b128 v[66:69], v199 offset:49152
	ds_read_b128 v[82:85], v199 offset:49280
	ds_read_b128 v[86:89], v200 offset:49152
	ds_read_b128 v[90:93], v200 offset:49280
	s_waitcnt lgkmcnt(3)
	v_mfma_f32_32x32x16_bf16 v[66:81], v[66:69], v[126:129], 0
	s_waitcnt lgkmcnt(1)
	v_mfma_f32_32x32x16_bf16 v[66:81], v[86:89], v[122:125], v[66:81]
	ds_read_b128 v[86:89], v201 offset:49152
	ds_read_b128 v[94:97], v201 offset:49280
	s_waitcnt lgkmcnt(1)
	v_mfma_f32_32x32x16_bf16 v[66:81], v[86:89], v[118:121], v[66:81]
	ds_read_b128 v[86:89], v202 offset:49152
	ds_read_b128 v[130:133], v202 offset:49280
	s_waitcnt lgkmcnt(1)
	v_mfma_f32_32x32x16_bf16 v[66:81], v[86:89], v[114:117], v[66:81]
	v_mfma_f32_32x32x16_bf16 v[66:81], v[82:85], v[110:113], v[66:81]
	ds_read_b128 v[82:85], v199 offset:57344
	ds_read_b128 v[138:141], v199 offset:57472
	ds_read_b128 v[228:231], v200 offset:57344
	ds_read_b128 v[232:235], v200 offset:57472
	ds_read_b128 v[236:239], v201 offset:57344
	ds_read_b128 v[240:243], v201 offset:57472
	ds_read_b128 v[244:247], v202 offset:57344
	ds_read_b128 v[248:251], v202 offset:57472
	v_mfma_f32_32x32x16_bf16 v[66:81], v[90:93], v[106:109], v[66:81]
	v_mfma_f32_32x32x16_bf16 v[66:81], v[94:97], v[102:105], v[66:81]
	s_waitcnt lgkmcnt(8)
	v_mfma_f32_32x32x16_bf16 v[66:81], v[130:133], v[98:101], v[66:81]
	v_mov_b32_e32 v165, v167
	v_lshl_add_u64 v[86:87], s[62:63], 0, v[164:165]
	v_mov_b32_e32 v177, v167
	v_mov_b32_e32 v179, v167
	v_lshl_add_u64 v[86:87], v[86:87], 0, v[176:177]
	v_lshl_add_u64 v[88:89], s[62:63], 0, v[178:179]
	v_lshl_add_u64 v[88:89], v[88:89], 0, v[176:177]
	global_load_dwordx4 v[130:133], v[86:87], off
	global_load_dwordx4 v[134:137], v[88:89], off
	v_lshl_add_u64 v[86:87], s[60:61], 0, v[164:165]
	v_lshl_add_u64 v[86:87], v[86:87], 0, v[176:177]
	v_lshl_add_u64 v[88:89], s[60:61], 0, v[178:179]
	v_lshl_add_u64 v[88:89], v[88:89], 0, v[176:177]
	global_load_dwordx4 v[142:145], v[86:87], off
	global_load_dwordx4 v[146:149], v[88:89], off
	s_waitcnt lgkmcnt(7)
	v_mfma_f32_32x32x16_bf16 v[82:97], v[82:85], v[126:129], 0
	v_mov_b32_e32 v187, v167
	v_mov_b32_e32 v181, v167
	s_waitcnt lgkmcnt(5)
	v_mfma_f32_32x32x16_bf16 v[82:97], v[228:231], v[122:125], v[82:97]
	s_waitcnt lgkmcnt(3)
	v_mfma_f32_32x32x16_bf16 v[82:97], v[236:239], v[118:121], v[82:97]
	s_waitcnt lgkmcnt(1)
	v_mfma_f32_32x32x16_bf16 v[82:97], v[244:247], v[114:117], v[82:97]
	v_mfma_f32_32x32x16_bf16 v[82:97], v[138:141], v[110:113], v[82:97]
	v_lshlrev_b64 v[110:111], 11, v[186:187]
	v_lshl_add_u64 v[110:111], s[10:11], 0, v[110:111]
	v_lshl_add_u64 v[138:139], v[110:111], 0, v[180:181]
	v_mfma_f32_32x32x16_bf16 v[82:97], v[232:235], v[106:109], v[82:97]
	global_load_dwordx4 v[126:129], v[138:139], off
	global_load_dwordx4 v[122:125], v[138:139], off offset:32
	global_load_dwordx4 v[118:121], v[138:139], off offset:64
	global_load_dwordx4 v[114:117], v[138:139], off offset:96
	global_load_dwordx4 v[110:113], v[138:139], off offset:128
	global_load_dwordx4 v[106:109], v[138:139], off offset:160
	v_mfma_f32_32x32x16_bf16 v[82:97], v[240:243], v[102:105], v[82:97]
	global_load_dwordx4 v[102:105], v[138:139], off offset:192
	s_nop 0
	global_load_dwordx4 v[138:141], v[138:139], off offset:224
	s_waitcnt lgkmcnt(0)
	v_mfma_f32_32x32x16_bf16 v[82:97], v[248:251], v[98:101], v[82:97]
	v_add_f32_e32 v98, 0, v219
	v_add_f32_e32 v98, v220, v98
	v_add_f32_e32 v98, v221, v98
	v_add_f32_e32 v98, v222, v98
	v_add_f32_e32 v98, v223, v98
	v_add_f32_e32 v98, v225, v98
	v_add_f32_e32 v98, v224, v98
	v_add_f32_e32 v98, v226, v98
	v_add_f32_e32 v98, v211, v98
	v_add_f32_e32 v98, v212, v98
	v_add_f32_e32 v98, v213, v98
	v_add_f32_e32 v98, v215, v98
	v_exp_f32_e32 v100, v194
	v_add_f32_e32 v98, v214, v98
	v_exp_f32_e32 v101, v195
	v_add_f32_e32 v98, v216, v98
	v_exp_f32_e32 v165, v192
	v_add_f32_e32 v98, v217, v98
	v_exp_f32_e32 v172, v193
	v_add_f32_e32 v98, v218, v98
	v_exp_f32_e32 v173, v158
	v_add_f32_e32 v98, v100, v98
	v_exp_f32_e32 v174, v159
	v_add_f32_e32 v98, v101, v98
	v_exp_f32_e32 v175, v154
	v_add_f32_e32 v98, v165, v98
	v_exp_f32_e32 v177, v155
	v_add_f32_e32 v98, v172, v98
	v_exp_f32_e32 v179, v150
	v_add_f32_e32 v98, v173, v98
	v_exp_f32_e32 v181, v151
	v_add_f32_e32 v98, v174, v98
	v_exp_f32_e32 v186, v160
	v_add_f32_e32 v98, v175, v98
	v_exp_f32_e32 v187, v161
	v_add_f32_e32 v98, v177, v98
	v_exp_f32_e32 v192, v156
	v_add_f32_e32 v98, v179, v98
	v_exp_f32_e32 v193, v157
	v_add_f32_e32 v98, v181, v98
	v_exp_f32_e32 v194, v152
	v_add_f32_e32 v98, v186, v98
	v_exp_f32_e32 v195, v153
	v_add_f32_e32 v98, v187, v98
	v_add_f32_e32 v98, v192, v98
	v_add_f32_e32 v98, v193, v98
	v_add_f32_e32 v98, v194, v98
	v_add_f32_e32 v98, v98, v195
	v_mov_b32_e32 v99, v98
	v_cvt_pk_bf16_f32 v150, v219, v220
	v_cvt_pk_bf16_f32 v151, v221, v222
	v_cvt_pk_bf16_f32 v152, v223, v225
	v_cvt_pk_bf16_f32 v153, v224, v226
	v_permlane32_swap_b32_e32 v98, v99
	v_permlane32_swap_b32_e32 v150, v152
	v_permlane32_swap_b32_e32 v151, v153
	v_cvt_pk_bf16_f32 v154, v211, v212
	v_cvt_pk_bf16_f32 v155, v213, v215
	v_cvt_pk_bf16_f32 v156, v214, v216
	v_cvt_pk_bf16_f32 v157, v217, v218
	v_cvt_pk_bf16_f32 v158, v100, v101
	v_cvt_pk_bf16_f32 v159, v165, v172
	v_cvt_pk_bf16_f32 v160, v173, v174
	v_cvt_pk_bf16_f32 v161, v175, v177
	v_cvt_pk_bf16_f32 v190, v179, v181
	v_cvt_pk_bf16_f32 v191, v186, v187
	v_cvt_pk_bf16_f32 v192, v192, v193
	v_cvt_pk_bf16_f32 v193, v194, v195
	v_permlane32_swap_b32_e32 v154, v156
	v_permlane32_swap_b32_e32 v155, v157
	v_permlane32_swap_b32_e32 v158, v160
	v_permlane32_swap_b32_e32 v159, v161
	v_permlane32_swap_b32_e32 v190, v192
	v_permlane32_swap_b32_e32 v191, v193
	ds_read_b64_tr_b16 v[208:209], v1 offset:0
	ds_read_b64_tr_b16 v[210:211], v1 offset:0x800
	ds_read_b64_tr_b16 v[212:213], v1 offset:0x1000
	ds_read_b64_tr_b16 v[214:215], v1 offset:0x1800
	ds_read_b64_tr_b16 v[216:217], v1 offset:0x2000
	ds_read_b64_tr_b16 v[218:219], v1 offset:0x2800
	ds_read_b64_tr_b16 v[220:221], v1 offset:0x3000
	ds_read_b64_tr_b16 v[222:223], v1 offset:0x3800
	s_waitcnt lgkmcnt(0)
; __device__ __forceinline__ void sel_mask_tile(f32x16& p0, f32x16& p1, unsigned wlo, unsigned whi, int hi) {
;     const unsigned NEGB = 0xff800000u;
;     const unsigned lo = wlo >> (4 * hi), h2 = whi >> (4 * hi);
; #pragma unroll
;     for (int r = 0; r < 16; ++r) {
;         const int c = (r & 3) + 8 * (r >> 2);
;         const unsigned m0 = (unsigned)__builtin_amdgcn_sbfe((int)lo, c, 1), m1 = (unsigned)__builtin_amdgcn_sbfe((int)h2, c, 1);
;         p0[r] = __uint_as_float((__float_as_uint(p0[r]) & m0) | (NEGB & ~m0));
;         p1[r] = __uint_as_float((__float_as_uint(p1[r]) & m1) | (NEGB & ~m1));
;     }
; }
; __device__ __forceinline__ void partialSM(f32x16& p0, f32x16& p1, float& m_reg, float& mn, float& alpha) {
;     float pmax = p0[0];
; #pragma unroll
;     for (int r = 1; r < 16; ++r) pmax = fmaxf(pmax, p0[r]);
; #pragma unroll
;     for (int r = 0; r < 16; ++r) pmax = fmaxf(pmax, p1[r]);
;     { auto rr = __builtin_amdgcn_permlane32_swap(__float_as_uint(pmax), __float_as_uint(pmax), false, false);
;       pmax = fmaxf(__uint_as_float(rr[0]), __uint_as_float(rr[1])); }
;     constexpr float C2 = 1.4426950408889634f * SCALE;
;     if (__builtin_expect(__all((pmax - m_reg) * SCALE <= THR), 1)) { mn = m_reg; alpha = 1.f; }
;     else { mn = fmaxf(m_reg, pmax); alpha = __builtin_amdgcn_exp2f((m_reg - mn) * C2); m_reg = mn; }
; template <int VB>
; __device__ __forceinline__ void pv_tile(f32x16* o, int vb0, bf16x8 pa0, bf16x8 pa1, bf16x8 pa2, bf16x8 pa3) {
;     ...
;     PV_D0(0); PV_D0(1); PV_D0(2); PV_D0(3);
	s_nop 0
	v_mfma_f32_32x32x16_bf16 v[2:17], v[150:153], v[208:211], v[2:17]
	ds_read_b64_tr_b16 v[208:209], v1 offset:0x200
	ds_read_b64_tr_b16 v[210:211], v1 offset:0xa00
	v_mfma_f32_32x32x16_bf16 v[2:17], v[154:157], v[212:215], v[2:17]
	ds_read_b64_tr_b16 v[212:213], v1 offset:0x1200
	ds_read_b64_tr_b16 v[214:215], v1 offset:0x1a00
	v_mfma_f32_32x32x16_bf16 v[2:17], v[158:161], v[216:219], v[2:17]
	ds_read_b64_tr_b16 v[216:217], v1 offset:0x2200
	ds_read_b64_tr_b16 v[218:219], v1 offset:0x2a00
	ds_read_b64_tr_b16 v[224:225], v1 offset:0x3200
	ds_read_b64_tr_b16 v[226:227], v1 offset:0x3a00
	s_waitcnt lgkmcnt(0)
	v_mfma_f32_32x32x16_bf16 v[2:17], v[190:193], v[220:223], v[2:17]
	v_mfma_f32_32x32x16_bf16 v[50:65], v[150:153], v[208:211], v[50:65]
	ds_read_b64_tr_b16 v[208:209], v1 offset:0x400
	ds_read_b64_tr_b16 v[210:211], v1 offset:0xc00
	v_mfma_f32_32x32x16_bf16 v[50:65], v[154:157], v[212:215], v[50:65]
	ds_read_b64_tr_b16 v[212:213], v1 offset:0x1400
	ds_read_b64_tr_b16 v[214:215], v1 offset:0x1c00
	v_mfma_f32_32x32x16_bf16 v[50:65], v[158:161], v[216:219], v[50:65]
	ds_read_b64_tr_b16 v[216:217], v1 offset:0x2400
	ds_read_b64_tr_b16 v[218:219], v1 offset:0x2c00
	ds_read_b64_tr_b16 v[220:221], v1 offset:0x3400
	ds_read_b64_tr_b16 v[222:223], v1 offset:0x3c00
	s_waitcnt lgkmcnt(0)
	v_mfma_f32_32x32x16_bf16 v[50:65], v[190:193], v[224:227], v[50:65]
	v_mfma_f32_32x32x16_bf16 v[34:49], v[150:153], v[208:211], v[34:49]
	ds_read_b64_tr_b16 v[208:209], v1 offset:0x600
	ds_read_b64_tr_b16 v[210:211], v1 offset:0xe00
	v_mfma_f32_32x32x16_bf16 v[34:49], v[154:157], v[212:215], v[34:49]
	ds_read_b64_tr_b16 v[212:213], v1 offset:0x1600
	ds_read_b64_tr_b16 v[214:215], v1 offset:0x1e00
	v_mfma_f32_32x32x16_bf16 v[34:49], v[158:161], v[216:219], v[34:49]
	ds_read_b64_tr_b16 v[216:217], v1 offset:0x2600
	ds_read_b64_tr_b16 v[218:219], v1 offset:0x2e00
	ds_read_b64_tr_b16 v[224:225], v1 offset:0x3600
	ds_read_b64_tr_b16 v[226:227], v1 offset:0x3e00
	s_waitcnt lgkmcnt(0)
	v_mfma_f32_32x32x16_bf16 v[34:49], v[190:193], v[220:223], v[34:49]
	s_waitcnt vmcnt(12)
	v_lshrrev_b32_e32 v165, v163, v188
	v_lshrrev_b32_e32 v172, v163, v189
	v_bfe_i32 v100, v165, 0, 1
	v_bfe_i32 v101, v172, 0, 1
	v_bitop3_b32 v100, v66, s74, v100 bitop3:0xe4
	v_bfe_i32 v66, v165, 1, 1
	v_bitop3_b32 v82, v82, s74, v101 bitop3:0xe4
	v_mfma_f32_32x32x16_bf16 v[18:33], v[150:153], v[208:211], v[18:33]
	v_bfe_i32 v150, v172, 1, 1
	v_bitop3_b32 v101, v67, s74, v66 bitop3:0xe4
	v_bfe_i32 v66, v165, 2, 1
	v_bitop3_b32 v67, v83, s74, v150 bitop3:0xe4
	v_bfe_i32 v150, v172, 2, 1
	v_bitop3_b32 v83, v68, s74, v66 bitop3:0xe4
	v_bfe_i32 v66, v165, 3, 1
	v_bitop3_b32 v68, v84, s74, v150 bitop3:0xe4
	v_bfe_i32 v84, v172, 3, 1
	v_bitop3_b32 v150, v69, s74, v66 bitop3:0xe4
	v_bfe_i32 v66, v165, 8, 1
	v_bitop3_b32 v69, v85, s74, v84 bitop3:0xe4
	v_bfe_i32 v84, v172, 8, 1
	v_bitop3_b32 v151, v70, s74, v66 bitop3:0xe4
	v_bfe_i32 v66, v165, 9, 1
	v_bitop3_b32 v70, v86, s74, v84 bitop3:0xe4
	v_bfe_i32 v84, v172, 9, 1
	v_bitop3_b32 v152, v71, s74, v66 bitop3:0xe4
	v_bfe_i32 v66, v165, 10, 1
	v_bitop3_b32 v71, v87, s74, v84 bitop3:0xe4
	v_bfe_i32 v84, v172, 10, 1
	v_bitop3_b32 v87, v72, s74, v66 bitop3:0xe4
	v_bfe_i32 v66, v165, 11, 1
	v_bitop3_b32 v72, v88, s74, v84 bitop3:0xe4
	v_bfe_i32 v84, v172, 11, 1
	v_bitop3_b32 v88, v73, s74, v66 bitop3:0xe4
	v_bfe_i32 v66, v165, 16, 1
	v_bitop3_b32 v84, v89, s74, v84 bitop3:0xe4
	v_bfe_i32 v73, v172, 16, 1
	v_bitop3_b32 v89, v74, s74, v66 bitop3:0xe4
	v_bfe_i32 v66, v165, 17, 1
	v_bitop3_b32 v85, v90, s74, v73 bitop3:0xe4
	v_bfe_i32 v73, v172, 17, 1
	v_bitop3_b32 v90, v75, s74, v66 bitop3:0xe4
	v_bfe_i32 v66, v165, 18, 1
	v_bitop3_b32 v86, v91, s74, v73 bitop3:0xe4
	v_bfe_i32 v73, v172, 18, 1
	v_bitop3_b32 v91, v76, s74, v66 bitop3:0xe4
	v_bfe_i32 v66, v165, 19, 1
	v_bitop3_b32 v76, v92, s74, v73 bitop3:0xe4
	v_bfe_i32 v73, v172, 19, 1
	v_bitop3_b32 v92, v77, s74, v66 bitop3:0xe4
	v_bfe_i32 v66, v165, 24, 1
	v_bitop3_b32 v77, v93, s74, v73 bitop3:0xe4
	v_bitop3_b32 v93, v78, s74, v66 bitop3:0xe4
	v_bfe_i32 v66, v165, 25, 1
	v_bitop3_b32 v79, v79, s74, v66 bitop3:0xe4
	v_bfe_i32 v66, v165, 26, 1
	v_bfe_i32 v73, v172, 24, 1
	v_bitop3_b32 v80, v80, s74, v66 bitop3:0xe4
	v_bfe_i32 v66, v165, 27, 1
	v_bitop3_b32 v78, v94, s74, v73 bitop3:0xe4
	v_bitop3_b32 v81, v81, s74, v66 bitop3:0xe4
	v_max_f32_e32 v66, v101, v101
	v_max_f32_e32 v94, v100, v100
	v_max_f32_e32 v66, v94, v66
	v_max3_f32 v66, v66, v83, v150
	v_max3_f32 v66, v66, v151, v152
	v_max3_f32 v66, v66, v87, v88
	v_max3_f32 v66, v66, v89, v90
	v_max3_f32 v66, v66, v91, v92
	v_max3_f32 v66, v66, v93, v79
	v_mfma_f32_32x32x16_bf16 v[18:33], v[154:157], v[212:215], v[18:33]
	v_max3_f32 v66, v66, v80, v81
	v_max3_f32 v66, v66, v82, v67
	v_max3_f32 v66, v66, v68, v69
	v_max3_f32 v66, v66, v70, v71
	v_max3_f32 v66, v66, v72, v84
	v_bfe_i32 v73, v172, 25, 1
	v_max3_f32 v66, v66, v85, v86
	v_bitop3_b32 v73, v95, s74, v73 bitop3:0xe4
	v_bfe_i32 v74, v172, 26, 1
	v_bfe_i32 v75, v172, 27, 1
	v_max3_f32 v66, v66, v76, v77
	v_bitop3_b32 v74, v96, s74, v74 bitop3:0xe4
	v_bitop3_b32 v75, v97, s74, v75 bitop3:0xe4
	v_max3_f32 v66, v66, v78, v73
	v_mfma_f32_32x32x16_bf16 v[18:33], v[158:161], v[216:219], v[18:33]
	v_max3_f32 v66, v66, v74, v75
	v_mov_b32_e32 v94, v66
	s_nop 1
	v_permlane32_swap_b32_e32 v66, v94
	v_max_f32_e32 v94, v94, v94
	v_max_f32_e32 v66, v66, v66
	v_max_f32_e32 v66, v66, v94
	v_sub_f32_e32 v94, v66, v206
	v_mul_f32_e32 v95, 0x3db504f3, v94
	v_max_f32_e32 v94, v206, v206
	v_max_f32_e32 v94, v94, v66
	v_mfma_f32_32x32x16_bf16 v[18:33], v[190:193], v[224:227], v[18:33]
	v_sub_f32_e32 v66, v206, v94
	v_mul_f32_e32 v66, 0x3e0293ee, v66
	v_exp_f32_e32 v66, v66
	v_cmp_ge_f32_e32 vcc, s75, v95
	s_cmp_eq_u64 vcc, exec
	s_cselect_b64 s[6:7], -1, 0
	v_cndmask_b32_e64 v66, v66, 1.0, s[6:7]
	v_cmp_gt_f32_e32 vcc, 1.0, v66
	s_barrier
	s_cbranch_vccz .LBB0_1317
	s_and_saveexec_b64 s[36:37], s[0:1]
	ds_write_b32 v185, v66 offset:128
	s_or_b64 exec, exec, s[36:37]
	s_waitcnt lgkmcnt(0)
	ds_read_b128 v[154:157], v183 offset:224
	ds_read_b128 v[158:161], v183 offset:192
	ds_read_b128 v[172:175], v183 offset:160
	ds_read_b128 v[186:189], v183 offset:128
	s_waitcnt lgkmcnt(3)
	v_pk_mul_f32 v[16:17], v[16:17], v[156:157]
	s_waitcnt lgkmcnt(2)
	v_pk_mul_f32 v[12:13], v[12:13], v[160:161]
	s_waitcnt lgkmcnt(1)
	v_pk_mul_f32 v[8:9], v[8:9], v[174:175]
	s_waitcnt lgkmcnt(0)
	v_pk_mul_f32 v[4:5], v[4:5], v[188:189]
	v_pk_mul_f32 v[14:15], v[14:15], v[154:155]
	v_pk_mul_f32 v[10:11], v[10:11], v[158:159]
	v_pk_mul_f32 v[6:7], v[6:7], v[172:173]
	v_pk_mul_f32 v[2:3], v[2:3], v[186:187]
	v_pk_mul_f32 v[64:65], v[64:65], v[156:157]
	v_pk_mul_f32 v[60:61], v[60:61], v[160:161]
	v_pk_mul_f32 v[56:57], v[56:57], v[174:175]
	v_pk_mul_f32 v[52:53], v[52:53], v[188:189]
	v_pk_mul_f32 v[62:63], v[62:63], v[154:155]
	v_pk_mul_f32 v[58:59], v[58:59], v[158:159]
	v_pk_mul_f32 v[54:55], v[54:55], v[172:173]
	v_pk_mul_f32 v[50:51], v[50:51], v[186:187]
	v_pk_mul_f32 v[48:49], v[48:49], v[156:157]
	v_pk_mul_f32 v[44:45], v[44:45], v[160:161]
	v_pk_mul_f32 v[40:41], v[40:41], v[174:175]
	v_pk_mul_f32 v[36:37], v[36:37], v[188:189]
	v_pk_mul_f32 v[46:47], v[46:47], v[154:155]
	v_pk_mul_f32 v[42:43], v[42:43], v[158:159]
	v_pk_mul_f32 v[38:39], v[38:39], v[172:173]
	v_pk_mul_f32 v[34:35], v[34:35], v[186:187]
	v_pk_mul_f32 v[32:33], v[32:33], v[156:157]
	v_pk_mul_f32 v[28:29], v[28:29], v[160:161]
	v_pk_mul_f32 v[24:25], v[24:25], v[174:175]
	v_pk_mul_f32 v[20:21], v[20:21], v[188:189]
	v_pk_mul_f32 v[30:31], v[30:31], v[154:155]
	v_pk_mul_f32 v[26:27], v[26:27], v[158:159]
	v_pk_mul_f32 v[22:23], v[22:23], v[172:173]
	v_pk_mul_f32 v[18:19], v[18:19], v[186:187]
